# scan2: row groups of one (b,h) placed on one XCD so P_c is shared in L2
# speedup vs baseline: 1.1127x; 1.0066x over previous
.Lsc2_unit:
	s_and_b32 s0, s10, 7
	s_lshl_b32 s0, s0, 5
	s_lshr_b32 s1, s10, 3
	s_or_b32 s6, s0, s1
	s_andn2_b32 s0, s6, 3
	s_lshl_b32 s0, s0, 17
	s_and_b32 s1, s6, 3
	s_lshl_b32 s1, s1, 12
	s_add_u32 s4, s2, s0
	s_addc_u32 s5, s3, 0
	s_add_u32 s4, s4, s1
	s_addc_u32 s5, s5, 0
	s_sub_u32 vcc_lo, 0x2000000, s1
	s_mov_b64 s[8:9], s[4:5]
	s_barrier
	s_add_u32 s6, s4, 0x0
	s_addc_u32 s7, s5, 0
	global_load_dwordx4 v[16:19], v105, s[6:7]
	s_add_u32 s6, s6, vcc_lo
	s_addc_u32 s7, s7, 0
	global_load_dword v0, v104, s[6:7]
	global_load_dword v1, v104, s[6:7] offset:256
	global_load_dword v2, v104, s[6:7] offset:512
	global_load_dword v3, v104, s[6:7] offset:768
	global_load_dword v4, v104, s[6:7] offset:1024
	global_load_dword v5, v104, s[6:7] offset:1280
	global_load_dword v6, v104, s[6:7] offset:1536
	global_load_dword v7, v104, s[6:7] offset:1792
	global_load_dword v8, v104, s[6:7] offset:2048
	global_load_dword v9, v104, s[6:7] offset:2304
	global_load_dword v10, v104, s[6:7] offset:2560
	global_load_dword v11, v104, s[6:7] offset:2816
	global_load_dword v12, v104, s[6:7] offset:3072
	global_load_dword v13, v104, s[6:7] offset:3328
	global_load_dword v14, v104, s[6:7] offset:3584
	global_load_dword v15, v104, s[6:7] offset:3840
	s_add_u32 s6, s4, 0x4000
	s_addc_u32 s7, s5, 0
	global_load_dwordx4 v[36:39], v105, s[6:7]
	s_add_u32 s6, s6, vcc_lo
	s_addc_u32 s7, s7, 0
	global_load_dword v20, v104, s[6:7]
	global_load_dword v21, v104, s[6:7] offset:256
	global_load_dword v22, v104, s[6:7] offset:512
	global_load_dword v23, v104, s[6:7] offset:768
	global_load_dword v24, v104, s[6:7] offset:1024
	global_load_dword v25, v104, s[6:7] offset:1280
	global_load_dword v26, v104, s[6:7] offset:1536
	global_load_dword v27, v104, s[6:7] offset:1792
	global_load_dword v28, v104, s[6:7] offset:2048
	global_load_dword v29, v104, s[6:7] offset:2304
	global_load_dword v30, v104, s[6:7] offset:2560
	global_load_dword v31, v104, s[6:7] offset:2816
	global_load_dword v32, v104, s[6:7] offset:3072
	global_load_dword v33, v104, s[6:7] offset:3328
	global_load_dword v34, v104, s[6:7] offset:3584
	global_load_dword v35, v104, s[6:7] offset:3840
	s_add_u32 s6, s4, 0x8000
	s_addc_u32 s7, s5, 0
	global_load_dwordx4 v[56:59], v105, s[6:7]
	s_add_u32 s6, s6, vcc_lo
	s_addc_u32 s7, s7, 0
	global_load_dword v40, v104, s[6:7]
	global_load_dword v41, v104, s[6:7] offset:256
	global_load_dword v42, v104, s[6:7] offset:512
	global_load_dword v43, v104, s[6:7] offset:768
	global_load_dword v44, v104, s[6:7] offset:1024
	global_load_dword v45, v104, s[6:7] offset:1280
	global_load_dword v46, v104, s[6:7] offset:1536
	global_load_dword v47, v104, s[6:7] offset:1792
	global_load_dword v48, v104, s[6:7] offset:2048
	global_load_dword v49, v104, s[6:7] offset:2304
	global_load_dword v50, v104, s[6:7] offset:2560
	global_load_dword v51, v104, s[6:7] offset:2816
	global_load_dword v52, v104, s[6:7] offset:3072
	global_load_dword v53, v104, s[6:7] offset:3328
	global_load_dword v54, v104, s[6:7] offset:3584
	global_load_dword v55, v104, s[6:7] offset:3840
	ds_write_b128 v107, v[112:115] offset:4352
	s_mov_b32 s0, 0
	s_waitcnt lgkmcnt(0)
	s_barrier
